# code placement: attention loop and all following code shifted by 4 bytes with dead padding so the hot blocks start 8-byte aligned
# baseline (speedup 1.0000x reference)
; __device__ __forceinline__ void attn_unit(const Params& P, unsigned char* lds, int h, int qb) {
;     ...
;     constexpr int KROW = 208, VROW = 136, KBUF = 64 * KROW, VBUF = 64 * VROW;
;     constexpr float THR = 8.0f;
;     const int q0 = qb * 256, qw0 = q0 + wave * 32, NT = (q0 + 256) >> 6, qg = qw0 + r32;
;     const int ntw = (qw0 + 31) / 64 + 1;
;     const int kkey = tid >> 3, kch = tid & 7, rkey = (tid & 255) >> 2, rch = tid & 3;
;     const bf16_t* kn_src = KN + (size_t)kkey * 512 + h * 64 + kch * 8;
;     const bf16_t* kr_src = KR + (size_t)rkey * 32 + rch * 8;
;     const bf16_t* vt_src = VT + (size_t)(h * 64 + kkey) * T + kch * 8;
;     const int kn_dst = kkey * KROW + kch * 16, kr_dst = rkey * KROW + 128 + rch * 16, vt_dst = 2 * KBUF + kkey * VROW + kch * 16;
;     const bool has_kr = tid < 256;
;     bf16x8 qr[6];
; #pragma unroll
;     for (int d0 = 0; d0 < 6; ++d0) qr[d0] = *(const bf16x8*)(Q + (size_t)(qw0 + r32) * 768 + h * 96 + d0 * 16 + hi * 8);
;     f32x16 o0, o1, negm;
; #pragma unroll
;     for (int r = 0; r < 16; ++r) { o0[r] = 0.f; o1[r] = 0.f; negm[r] = 0.f; }
;     float m = 0.f, lsum = 0.f;
;     v4u rkn, rkr = (v4u){0u, 0u, 0u, 0u}, rvt;
;     ...
;     __syncthreads();
.LBB0_876:
	s_sub_i32 s8, 0x5f00, s10
	s_lshr_b32 s17, s8, 6
	s_ashr_i32 s8, s15, 31
	s_lshr_b32 s8, s8, 26
	s_add_i32 s8, s8, s15
	s_add_i32 s8, s8, 31
	s_ashr_i32 s18, s8, 6
	v_add_u32_e32 v251, v32, v0
	v_lshlrev_b32_e32 v0, 4, v36
	s_movk_i32 s8, 0xfc0
	v_lshlrev_b32_e32 v3, 3, v38
	v_mul_i32_i24_e32 v4, 0xffffffb8, v37
	v_and_or_b32 v0, v0, s8, v32
	v_add3_u32 v250, v2, v4, v3
	v_lshl_add_u64 v[2:3], s[6:7], 0, v[0:1]
	s_mov_b64 s[8:9], 0x1ae03000
	v_lshl_add_u64 v[202:203], v[2:3], 0, s[8:9]
	v_lshl_add_u64 v[2:3], v[12:13], 0, s[92:93]
	v_mov_b32_e32 v15, v1
	v_lshl_add_u64 v[2:3], v[2:3], 0, v[14:15]
	v_lshl_add_u64 v[2:3], s[6:7], 0, v[2:3]
	s_mov_b64 s[8:9], 0x17630000
	v_lshl_add_u64 v[204:205], v[2:3], 0, s[8:9]
	v_lshl_add_u64 v[2:3], v[34:35], 0, v[14:15]
	v_lshl_add_u64 v[2:3], s[6:7], 0, v[2:3]
	s_mov_b64 s[8:9], 0x1d000100
	v_mov_b32_e32 v14, v1
	v_lshl_add_u64 v[206:207], v[2:3], 0, s[8:9]
	v_mov_b32_e32 v0, v1
	v_mov_b32_e32 v2, v1
	v_mov_b32_e32 v3, v1
	v_mov_b32_e32 v4, v1
	v_mov_b32_e32 v5, v1
	v_mov_b32_e32 v6, v1
	v_mov_b32_e32 v7, v1
	v_mov_b32_e32 v8, v1
	v_mov_b32_e32 v9, v1
	v_mov_b32_e32 v10, v1
	v_mov_b32_e32 v11, v1
	v_mov_b32_e32 v12, v1
	v_mov_b32_e32 v13, v1
	v_mov_b32_e32 v236, 0
	v_mov_b64_e32 v[62:63], v[14:15]
	v_mov_b64_e32 v[46:47], v[14:15]
	s_max_u32 s19, s17, 1
	s_mov_b32 s21, 0
	s_movk_i32 s20, 0x7f
	v_mov_b64_e32 v[60:61], v[12:13]
	v_mov_b64_e32 v[58:59], v[10:11]
	v_mov_b64_e32 v[56:57], v[8:9]
	v_mov_b64_e32 v[54:55], v[6:7]
	v_mov_b64_e32 v[52:53], v[4:5]
	v_mov_b64_e32 v[50:51], v[2:3]
	v_mov_b64_e32 v[48:49], v[0:1]
	v_mov_b64_e32 v[44:45], v[12:13]
	v_mov_b64_e32 v[42:43], v[10:11]
	v_mov_b64_e32 v[40:41], v[8:9]
	v_mov_b64_e32 v[38:39], v[6:7]
	v_mov_b64_e32 v[36:37], v[4:5]
	v_mov_b64_e32 v[34:35], v[2:3]
	v_mov_b64_e32 v[32:33], v[0:1]
	v_mov_b32_e32 v0, 0
	v_mov_b32_e32 v64, 0
	v_mov_b32_e32 v65, v236
	v_mov_b32_e32 v66, v236
	v_mov_b32_e32 v67, v236
	v_mov_b32_e32 v68, v236
	v_mov_b32_e32 v69, v236
	v_mov_b32_e32 v70, v236
	v_mov_b32_e32 v71, v236
	v_mov_b32_e32 v72, v236
	v_mov_b32_e32 v73, v236
	v_mov_b32_e32 v74, v236
	v_mov_b32_e32 v75, v236
	v_mov_b32_e32 v76, v236
	v_mov_b32_e32 v77, v236
	v_mov_b32_e32 v78, v236
	v_mov_b32_e32 v79, v236
	s_barrier
	s_cmp_le_i32 s21, s18
	s_cselect_b64 s[8:9], -1, 0
	s_cmp_gt_i32 s21, s18
	s_cbranch_scc1 .LBB0_878
	s_branch .LBB0_885
	s_nop 0
